# aligned combo12 with arrival-rank-based background conversion, first 20 arrivers per XCC share the items, last twelve convert nothing
# baseline (speedup 1.0000x reference)
; #define LAS __attribute__((address_space(3)))
; __device__ __forceinline__ void cv_background(Frame& F, const CvPtrs& P, int s) {
;     ...
;     const int w = __builtin_amdgcn_readfirstlane(tv >> 6) - 1, lane = tv & 63, nbw = F.G * (NWAVES - 1);
;     LAS float* scr = (LAS float*)(F.lds + RING_OFF + (w + 1) * 16384);
;     const int sh_ = cv_bg_share(s), hi = (sh_ + 1) * CV_BG_PER < CV_BG_TOTAL ? (sh_ + 1) * CV_BG_PER : CV_BG_TOTAL;
;     for (int j = sh_ * CV_BG_PER + F.vcu * (NWAVES - 1) + w; j < hi; j += nbw) {
.Lbg_rank:
	v_readlane_b32 s5, v254, 48
	s_cmp_lg_u32 s5, 0
	s_cbranch_scc1 .Lbg_idx_done
	v_readlane_b32 s4, v255, 20
	s_cmp_ge_u32 s4, 64
	s_cbranch_scc1 .Lbg_idx_done
	s_cmp_ge_u32 s4, 20
	s_cbranch_scc1 .LBB0_1015
	s_lshl_b32 s4, s4, 3
	s_add_u32 s98, s4, s88
	s_movk_i32 s99, 0xa0
